# lever 1 waits at first consumer: attention-C tile head issues K-fragment / LUT reads in first-consumer order with a counted lgkmcnt per S MFMA
# baseline (speedup 1.0000x reference)
; #define FLAS __attribute__((address_space(3)))
; #define FA_SB() __builtin_amdgcn_sched_barrier(0)
; template <int MODE> __device__ __forceinline__ void attn_unit(FLAS unsigned char* lds, const Unit u) {
;     ...
;         if (MODE == 2) active = (k0 + 63 >= q0w - 1024) && (k0 <= q0w + 31 + 1024);
;         if (active) {
;             f32x16 p0, p1;
;             bf16x8 kf[8];
;             { const FLAS unsigned char* kb = lds + L_K + cur * KBUF;
; #pragma unroll
;               for (int d0 = 0; d0 < 4; ++d0) { const int ko = (2 * d0 + hi) * 1024 + ((r32 ^ (2 * d0 + hi)) * 16); kf[2 * d0] = *(const FLAS bf16x8*)(kb + ko); kf[2 * d0 + 1] = *(const FLAS bf16x8*)(kb + ko + 512); } }
;             float cb = 0.f; bool zinit = false;
;             if (MODE == 0) { const int dmin = k0 - (q0w + 31), dmax = k0 + 63 - q0w;
;                 if (dmin >= 559) { cb = L[LUT_C + 600]; zinit = true; } else if (dmax <= -559) { cb = L[LUT_C - 600]; zinit = true; } }
;             if (zinit) {
;                 const f32x16 z16 = {0.f,0.f,0.f,0.f,0.f,0.f,0.f,0.f,0.f,0.f,0.f,0.f,0.f,0.f,0.f,0.f};
;                 FA_SB();
;                 p0 = __builtin_amdgcn_mfma_f32_32x32x16_bf16(kf[0], qr[0], z16, 0, 0, 0); p1 = __builtin_amdgcn_mfma_f32_32x32x16_bf16(kf[1], qr[0], z16, 0, 0, 0);
; #pragma unroll
;                 for (int d0 = 1; d0 < 4; ++d0) { p0 = __builtin_amdgcn_mfma_f32_32x32x16_bf16(kf[2 * d0], qr[d0], p0, 0, 0, 0); p1 = __builtin_amdgcn_mfma_f32_32x32x16_bf16(kf[2 * d0 + 1], qr[d0], p1, 0, 0, 0); }
;             } else {
;                 if (MODE == 0 || MODE == 2) { const FLAS float* lp = L + (k0 - q + LUT_C + 4 * hi);
; #pragma unroll
;                     for (int r = 0; r < 16; ++r) { p0[r] = lp[(r & 3) + 8 * (r >> 2)]; p1[r] = lp[32 + (r & 3) + 8 * (r >> 2)]; }
;                 } else { const FLAS float* lp = L + ((t - gi + 7) * 128 + 63 - qc + 4 * hi);
; #pragma unroll
;                     for (int r = 0; r < 16; ++r) { const int kc = (r & 3) + 8 * (r >> 2) + 4 * hi;
;                         const float v0 = lp[(r & 3) + 8 * (r >> 2)], v1 = lp[32 + (r & 3) + 8 * (r >> 2)];
;                         p0[r] = ((unsigned)(kc - cstart) < 16u) ? v0 : NEG; p1[r] = ((unsigned)(kc + 32 - cstart) < 16u) ? v1 : NEG; } }
;                 FA_SB();
; #pragma unroll
.LBB0_498:
	s_and_b32 s24, s8, 1
	s_add_i32 s9, s22, 63
	s_cmp_ge_i32 s9, s12
	s_cselect_b64 s[34:35], -1, 0
	s_cmp_le_i32 s22, s21
	s_cselect_b64 s[38:39], -1, 0
	s_and_b64 s[34:35], s[34:35], s[38:39]
	s_andn2_b64 vcc, exec, s[34:35]
	s_cbranch_vccnz .LBB0_506
	s_lshl_b32 s9, s24, 13
	s_add_i32 s9, s9, 0
	v_add3_u32 v126, s9, v139, v140
	ds_read_b128 v[88:91], v126
	ds_read2_b32 v[32:33], v147 offset1:1
	ds_read2_b32 v[34:35], v147 offset0:2 offset1:3
	ds_read2_b32 v[36:37], v147 offset0:8 offset1:9
	ds_read2_b32 v[38:39], v147 offset0:10 offset1:11
	ds_read2_b32 v[40:41], v147 offset0:16 offset1:17
	ds_read2_b32 v[42:43], v147 offset0:18 offset1:19
	ds_read2_b32 v[44:45], v147 offset0:24 offset1:25
	ds_read2_b32 v[46:47], v147 offset0:26 offset1:27
	ds_read_b128 v[92:95], v126 offset:512
	ds_read2_b32 v[48:49], v147 offset0:32 offset1:33
	ds_read2_b32 v[50:51], v147 offset0:34 offset1:35
	ds_read2_b32 v[52:53], v147 offset0:40 offset1:41
	ds_read2_b32 v[54:55], v147 offset0:42 offset1:43
	ds_read2_b32 v[56:57], v147 offset0:48 offset1:49
	ds_read2_b32 v[58:59], v147 offset0:50 offset1:51
	ds_read2_b32 v[60:61], v147 offset0:56 offset1:57
	ds_read2_b32 v[62:63], v147 offset0:58 offset1:59
	v_add3_u32 v127, s9, v141, v142
	ds_read_b128 v[102:105], v127
	ds_read_b128 v[106:109], v127 offset:512
	v_add3_u32 v126, s9, v143, v144
	ds_read_b128 v[110:113], v126
	ds_read_b128 v[114:117], v126 offset:512
	v_add3_u32 v127, s9, v145, v146
	ds_read_b128 v[118:121], v127
	ds_read_b128 v[122:125], v127 offset:512
	s_xor_b64 s[6:7], s[6:7], -1
	s_waitcnt lgkmcnt(15)
	v_mfma_f32_32x32x16_bf16 v[32:47], v[88:91], v[64:67], v[32:47]
	s_mul_i32 s9, s24, 0x4800
	v_add_u32_e32 v149, s9, v138
	s_waitcnt lgkmcnt(6)
	v_mfma_f32_32x32x16_bf16 v[48:63], v[92:95], v[64:67], v[48:63]
	ds_read_b128 v[92:95], v149 offset:16384
	ds_read_b128 v[88:91], v149 offset:20992
	s_waitcnt lgkmcnt(7)
	v_mfma_f32_32x32x16_bf16 v[32:47], v[102:105], v[68:71], v[32:47]
	s_waitcnt lgkmcnt(6)
	v_mfma_f32_32x32x16_bf16 v[48:63], v[106:109], v[68:71], v[48:63]
	s_waitcnt lgkmcnt(5)
	v_mfma_f32_32x32x16_bf16 v[32:47], v[110:113], v[72:75], v[32:47]
	s_waitcnt lgkmcnt(4)
	v_mfma_f32_32x32x16_bf16 v[48:63], v[114:117], v[72:75], v[48:63]
	s_waitcnt lgkmcnt(3)
	v_mfma_f32_32x32x16_bf16 v[32:47], v[118:121], v[76:79], v[32:47]
	s_waitcnt lgkmcnt(2)
	v_mfma_f32_32x32x16_bf16 v[48:63], v[122:125], v[76:79], v[48:63]
	s_and_b32 s8, s8, 3
	s_cmp_lg_u32 s8, 0
	s_cselect_b64 s[8:9], -1, 0
	v_sub_f32_e32 v102, 0, v148
	s_and_b64 s[8:9], s[6:7], s[8:9]
	s_nop 5
	v_add_f32_e32 v132, v102, v32
	v_add_f32_e32 v133, v102, v33
	v_add_f32_e32 v120, v102, v48
	v_add_f32_e32 v121, v102, v49
	v_add_f32_e32 v130, v102, v34
	v_add_f32_e32 v131, v102, v35
	v_add_f32_e32 v116, v102, v50
	v_add_f32_e32 v117, v102, v51
	v_add_f32_e32 v128, v102, v36
	v_add_f32_e32 v129, v102, v37
	v_add_f32_e32 v114, v102, v52
	v_add_f32_e32 v115, v102, v53
	v_add_f32_e32 v126, v102, v38
	v_add_f32_e32 v127, v102, v39
	v_add_f32_e32 v110, v102, v54
	v_add_f32_e32 v111, v102, v55
	v_add_f32_e32 v124, v102, v40
	v_add_f32_e32 v125, v102, v41
	v_add_f32_e32 v108, v102, v56
	v_add_f32_e32 v109, v102, v57
	v_add_f32_e32 v122, v102, v42
	v_add_f32_e32 v123, v102, v43
	v_add_f32_e32 v106, v102, v58
	v_add_f32_e32 v107, v102, v59
	v_add_f32_e32 v118, v102, v44
	v_add_f32_e32 v119, v102, v45
	v_add_f32_e32 v104, v102, v60
	v_add_f32_e32 v105, v102, v61
	v_add_f32_e32 v112, v102, v46
	v_add_f32_e32 v113, v102, v47
	v_add_f32_e32 v103, v102, v63
	v_add_f32_e32 v102, v102, v62
	s_and_b64 vcc, exec, s[8:9]
	s_mov_b32 s25, 0x41000000
	s_cbranch_vccnz .LBB0_507
	v_max3_f32 v32, v121, v133, v116
	v_max3_f32 v33, v130, v117, v131
	v_max3_f32 v32, v32, v132, v120
	v_max3_f32 v33, v33, v114, v128
	v_max3_f32 v32, v32, v115, v129
	v_max3_f32 v33, v33, v110, v126
	v_max3_f32 v32, v32, v111, v127
	v_max3_f32 v33, v33, v108, v124
	v_max3_f32 v32, v32, v109, v125
	v_max3_f32 v33, v33, v106, v122
	v_max3_f32 v32, v32, v107, v123
	v_max3_f32 v33, v33, v104, v118
	v_max3_f32 v32, v32, v105, v119
	v_max3_f32 v33, v33, v102, v112
	v_max3_f32 v32, v32, v103, v113
	v_max_f32_e32 v32, v32, v33
	v_mov_b32_e32 v33, v32
	s_nop 1
	v_permlane32_swap_b32 v32, v33
	s_nop 1
	s_mov_b64 s[8:9], -1
	v_max_f32_e32 v164, v32, v33
	s_and_b64 vcc, exec, s[6:7]
	s_movk_i32 s38, 0x87f
	s_mov_b64 s[34:35], 0x800
	s_cbranch_vccz .LBB0_503
	v_cmp_lt_f32_e32 vcc, s25, v164
	s_cbranch_vccz .LBB0_508
	v_max_f32_e32 v32, v164, v164
	v_max_f32_e32 v167, 0, v32
	v_exp_f32_e64 v184, -v167
	v_add_f32_e32 v148, v148, v167
	v_sub_f32_e32 v166, v132, v167
	v_sub_f32_e32 v165, v133, v167
	v_pk_mul_f32 v[62:63], v[30:31], v[184:185] op_sel_hi:[1,0]
	v_pk_mul_f32 v[60:61], v[28:29], v[184:185] op_sel_hi:[1,0]
	v_pk_mul_f32 v[58:59], v[26:27], v[184:185] op_sel_hi:[1,0]
	v_pk_mul_f32 v[56:57], v[24:25], v[184:185] op_sel_hi:[1,0]
	v_pk_mul_f32 v[54:55], v[22:23], v[184:185] op_sel_hi:[1,0]
	v_pk_mul_f32 v[52:53], v[20:21], v[184:185] op_sel_hi:[1,0]
	v_pk_mul_f32 v[50:51], v[18:19], v[184:185] op_sel_hi:[1,0]
	v_pk_mul_f32 v[48:49], v[16:17], v[184:185] op_sel_hi:[1,0]
	v_pk_mul_f32 v[46:47], v[14:15], v[184:185] op_sel_hi:[1,0]
	v_pk_mul_f32 v[44:45], v[12:13], v[184:185] op_sel_hi:[1,0]
	v_pk_mul_f32 v[42:43], v[10:11], v[184:185] op_sel_hi:[1,0]
	v_pk_mul_f32 v[40:41], v[8:9], v[184:185] op_sel_hi:[1,0]
	v_pk_mul_f32 v[38:39], v[6:7], v[184:185] op_sel_hi:[1,0]
	v_pk_mul_f32 v[36:37], v[4:5], v[184:185] op_sel_hi:[1,0]
	v_pk_mul_f32 v[34:35], v[2:3], v[184:185] op_sel_hi:[1,0]
	v_pk_mul_f32 v[32:33], v[0:1], v[184:185] op_sel_hi:[1,0]
	v_sub_f32_e32 v163, v130, v167
	v_sub_f32_e32 v162, v131, v167
	v_sub_f32_e32 v161, v128, v167
	v_sub_f32_e32 v160, v129, v167
	v_sub_f32_e32 v159, v126, v167
	v_sub_f32_e32 v158, v127, v167
	v_sub_f32_e32 v157, v124, v167
	v_sub_f32_e32 v156, v125, v167
	v_sub_f32_e32 v155, v122, v167
	v_sub_f32_e32 v154, v123, v167
	v_sub_f32_e32 v153, v118, v167
	v_sub_f32_e32 v152, v119, v167
	v_sub_f32_e32 v151, v112, v167
	v_sub_f32_e32 v150, v113, v167
	v_sub_f32_e32 v182, v120, v167
	v_sub_f32_e32 v181, v121, v167
	v_sub_f32_e32 v180, v116, v167
	v_sub_f32_e32 v179, v117, v167
	v_sub_f32_e32 v178, v114, v167
	v_sub_f32_e32 v177, v115, v167
	v_sub_f32_e32 v176, v110, v167
	v_sub_f32_e32 v175, v111, v167
	v_sub_f32_e32 v174, v108, v167
	v_sub_f32_e32 v173, v109, v167
	v_sub_f32_e32 v172, v106, v167
	v_sub_f32_e32 v171, v107, v167
	v_sub_f32_e32 v170, v104, v167
	v_sub_f32_e32 v169, v105, v167
	v_sub_f32_e32 v168, v102, v167
	v_sub_f32_e32 v167, v103, v167
	v_mul_f32_e32 v183, v137, v184
	s_mov_b64 s[8:9], 0
